# v34 + gMLP spatial-gating epilogue rewritten: all 32 u-value loads in flight before one wait, then compute+store (was 32 serialized load-wait-store steps)
# speedup vs baseline: 1.0069x; 1.0069x over previous
; DI float bf2f(unsigned short u) { return __uint_as_float(((unsigned)u) << 16); }
; DI int crow(int i, int h) { return (i & 3) + 8 * (i >> 2) + 4 * h; }
; DI void phase_sgu(ArgsP AP, LAS unsigned char* lds) {
;     ...
; #pragma unroll
;             for (int ci = 0; ci < 2; ++ci)
; #pragma unroll
;                 for (int i = 0; i < 16; ++i) { const int t = 32 * tb + crow(i, h), c = g * 128 + 32 * (cb0 + ci) + r32; const size_t row = r0 + t;
;                     const float mixed = acc[ci][i] + gbs[g * 128 + t]; const float uv = bf2f(UV[row * 2048 + c]);
.LBB0_221:
	v_add_u32_e32 v32, s2, v40
	v_or_b32_e32 v87, s2, v154
	v_ashrrev_i32_e32 v33, 31, v32
	v_lshl_add_u64 v[146:147], v[32:33], 2, s[46:47]
	v_or_b32_e32 v32, s9, v87
	v_lshlrev_b32_e32 v96, 1, v32
	global_load_dwordx4 v[130:133], v[146:147], off
	global_load_dwordx4 v[134:137], v[146:147], off offset:32
	global_load_dwordx4 v[138:141], v[146:147], off offset:64
	global_load_dwordx4 v[142:145], v[146:147], off offset:96
	v_lshl_add_u64 v[150:151], s[0:1], 0, v[96:97]
	v_lshl_add_u64 v[152:153], s[16:17], 0, v[96:97]
	v_lshl_add_u64 v[148:149], s[22:23], 0, v[40:41]
	v_lshlrev_b64 v[148:149], 12, v[148:149]
	v_lshl_add_u64 v[148:149], v[150:151], 0, v[148:149]
	global_load_ushort v98, v[148:149], off
	global_load_ushort v99, v[148:149], off offset:64
	v_lshl_add_u64 v[148:149], s[22:23], 0, v[50:51]
	v_lshlrev_b64 v[148:149], 12, v[148:149]
	v_lshl_add_u64 v[148:149], v[150:151], 0, v[148:149]
	global_load_ushort v100, v[148:149], off
	global_load_ushort v101, v[148:149], off offset:64
	v_lshl_add_u64 v[148:149], s[22:23], 0, v[52:53]
	v_lshlrev_b64 v[148:149], 12, v[148:149]
	v_lshl_add_u64 v[148:149], v[150:151], 0, v[148:149]
	global_load_ushort v102, v[148:149], off
	global_load_ushort v103, v[148:149], off offset:64
	v_lshl_add_u64 v[148:149], s[22:23], 0, v[54:55]
	v_lshlrev_b64 v[148:149], 12, v[148:149]
	v_lshl_add_u64 v[148:149], v[150:151], 0, v[148:149]
	global_load_ushort v104, v[148:149], off
	global_load_ushort v105, v[148:149], off offset:64
	v_lshl_add_u64 v[148:149], s[22:23], 0, v[56:57]
	v_lshlrev_b64 v[148:149], 12, v[148:149]
	v_lshl_add_u64 v[148:149], v[150:151], 0, v[148:149]
	global_load_ushort v106, v[148:149], off
	global_load_ushort v107, v[148:149], off offset:64
	v_lshl_add_u64 v[148:149], s[22:23], 0, v[58:59]
	v_lshlrev_b64 v[148:149], 12, v[148:149]
	v_lshl_add_u64 v[148:149], v[150:151], 0, v[148:149]
	global_load_ushort v108, v[148:149], off
	global_load_ushort v109, v[148:149], off offset:64
	v_lshl_add_u64 v[148:149], s[22:23], 0, v[60:61]
	v_lshlrev_b64 v[148:149], 12, v[148:149]
	v_lshl_add_u64 v[148:149], v[150:151], 0, v[148:149]
	global_load_ushort v110, v[148:149], off
	global_load_ushort v111, v[148:149], off offset:64
	v_lshl_add_u64 v[148:149], s[22:23], 0, v[62:63]
	v_lshlrev_b64 v[148:149], 12, v[148:149]
	v_lshl_add_u64 v[148:149], v[150:151], 0, v[148:149]
	global_load_ushort v112, v[148:149], off
	global_load_ushort v113, v[148:149], off offset:64
	v_lshl_add_u64 v[148:149], s[22:23], 0, v[64:65]
	v_lshlrev_b64 v[148:149], 12, v[148:149]
	v_lshl_add_u64 v[148:149], v[150:151], 0, v[148:149]
	global_load_ushort v114, v[148:149], off
	global_load_ushort v115, v[148:149], off offset:64
	v_lshl_add_u64 v[148:149], s[22:23], 0, v[66:67]
	v_lshlrev_b64 v[148:149], 12, v[148:149]
	v_lshl_add_u64 v[148:149], v[150:151], 0, v[148:149]
	global_load_ushort v116, v[148:149], off
	global_load_ushort v117, v[148:149], off offset:64
	v_lshl_add_u64 v[148:149], s[22:23], 0, v[68:69]
	v_lshlrev_b64 v[148:149], 12, v[148:149]
	v_lshl_add_u64 v[148:149], v[150:151], 0, v[148:149]
	global_load_ushort v118, v[148:149], off
	global_load_ushort v119, v[148:149], off offset:64
	v_lshl_add_u64 v[148:149], s[22:23], 0, v[70:71]
	v_lshlrev_b64 v[148:149], 12, v[148:149]
	v_lshl_add_u64 v[148:149], v[150:151], 0, v[148:149]
	global_load_ushort v120, v[148:149], off
	global_load_ushort v121, v[148:149], off offset:64
	v_lshl_add_u64 v[148:149], s[22:23], 0, v[72:73]
	v_lshlrev_b64 v[148:149], 12, v[148:149]
	v_lshl_add_u64 v[148:149], v[150:151], 0, v[148:149]
	global_load_ushort v122, v[148:149], off
	global_load_ushort v123, v[148:149], off offset:64
	v_lshl_add_u64 v[148:149], s[22:23], 0, v[74:75]
	v_lshlrev_b64 v[148:149], 12, v[148:149]
	v_lshl_add_u64 v[148:149], v[150:151], 0, v[148:149]
	global_load_ushort v124, v[148:149], off
	global_load_ushort v125, v[148:149], off offset:64
	v_lshl_add_u64 v[148:149], s[22:23], 0, v[76:77]
	v_lshlrev_b64 v[148:149], 12, v[148:149]
	v_lshl_add_u64 v[148:149], v[150:151], 0, v[148:149]
	global_load_ushort v126, v[148:149], off
	global_load_ushort v127, v[148:149], off offset:64
	v_lshl_add_u64 v[148:149], s[22:23], 0, v[78:79]
	v_lshlrev_b64 v[148:149], 12, v[148:149]
	v_lshl_add_u64 v[148:149], v[150:151], 0, v[148:149]
	global_load_ushort v128, v[148:149], off
	global_load_ushort v129, v[148:149], off offset:64
	s_waitcnt vmcnt(0)
; DI unsigned pk2(float lo, float hi) { f32x2 v = {lo, hi}; bf16x2_t b = __builtin_convertvector(v, bf16x2_t); return __builtin_bit_cast(unsigned, b); }
; DI float bf2f(unsigned short u) { return __uint_as_float(((unsigned)u) << 16); }
; DI int crow(int i, int h) { return (i & 3) + 8 * (i >> 2) + 4 * h; }
; DI void phase_sgu(ArgsP AP, LAS unsigned char* lds) {
;     ...
;                 for (int i = 0; i < 16; ++i) { const int t = 32 * tb + crow(i, h), c = g * 128 + 32 * (cb0 + ci) + r32; const size_t row = r0 + t;
;                     const float mixed = acc[ci][i] + gbs[g * 128 + t]; const float uv = bf2f(UV[row * 2048 + c]);
;                     OA[row * DM + c] = (bf16)(pk2(uv * mixed, 0.f) & 0xffffu); }
	v_lshl_add_u64 v[148:149], s[22:23], 0, v[40:41]
	v_lshlrev_b64 v[148:149], 11, v[148:149]
	v_lshl_add_u64 v[148:149], v[152:153], 0, v[148:149]
	v_add_f32_e32 v32, v16, v130
	v_lshlrev_b32_e32 v34, 16, v98
	v_mul_f32_e32 v32, v32, v34
	v_cvt_pk_bf16_f32 v32, v32, s0
	global_store_short v[148:149], v32, off
	v_add_f32_e32 v33, v0, v130
	v_lshlrev_b32_e32 v35, 16, v99
	v_mul_f32_e32 v33, v33, v35
	v_cvt_pk_bf16_f32 v33, v33, s0
	global_store_short v[148:149], v33, off offset:64
	v_lshl_add_u64 v[148:149], s[22:23], 0, v[50:51]
	v_lshlrev_b64 v[148:149], 11, v[148:149]
	v_lshl_add_u64 v[148:149], v[152:153], 0, v[148:149]
	v_add_f32_e32 v32, v17, v131
	v_lshlrev_b32_e32 v34, 16, v100
	v_mul_f32_e32 v32, v32, v34
	v_cvt_pk_bf16_f32 v32, v32, s0
	global_store_short v[148:149], v32, off
	v_add_f32_e32 v33, v1, v131
	v_lshlrev_b32_e32 v35, 16, v101
	v_mul_f32_e32 v33, v33, v35
	v_cvt_pk_bf16_f32 v33, v33, s0
	global_store_short v[148:149], v33, off offset:64
	v_lshl_add_u64 v[148:149], s[22:23], 0, v[52:53]
	v_lshlrev_b64 v[148:149], 11, v[148:149]
	v_lshl_add_u64 v[148:149], v[152:153], 0, v[148:149]
	v_add_f32_e32 v32, v18, v132
	v_lshlrev_b32_e32 v34, 16, v102
	v_mul_f32_e32 v32, v32, v34
	v_cvt_pk_bf16_f32 v32, v32, s0
	global_store_short v[148:149], v32, off
	v_add_f32_e32 v33, v2, v132
	v_lshlrev_b32_e32 v35, 16, v103
	v_mul_f32_e32 v33, v33, v35
	v_cvt_pk_bf16_f32 v33, v33, s0
	global_store_short v[148:149], v33, off offset:64
	v_lshl_add_u64 v[148:149], s[22:23], 0, v[54:55]
	v_lshlrev_b64 v[148:149], 11, v[148:149]
	v_lshl_add_u64 v[148:149], v[152:153], 0, v[148:149]
	v_add_f32_e32 v32, v19, v133
	v_lshlrev_b32_e32 v34, 16, v104
	v_mul_f32_e32 v32, v32, v34
	v_cvt_pk_bf16_f32 v32, v32, s0
	global_store_short v[148:149], v32, off
	v_add_f32_e32 v33, v3, v133
	v_lshlrev_b32_e32 v35, 16, v105
	v_mul_f32_e32 v33, v33, v35
	v_cvt_pk_bf16_f32 v33, v33, s0
	global_store_short v[148:149], v33, off offset:64
	v_lshl_add_u64 v[148:149], s[22:23], 0, v[56:57]
	v_lshlrev_b64 v[148:149], 11, v[148:149]
	v_lshl_add_u64 v[148:149], v[152:153], 0, v[148:149]
	v_add_f32_e32 v32, v20, v134
	v_lshlrev_b32_e32 v34, 16, v106
	v_mul_f32_e32 v32, v32, v34
	v_cvt_pk_bf16_f32 v32, v32, s0
	global_store_short v[148:149], v32, off
	v_add_f32_e32 v33, v4, v134
	v_lshlrev_b32_e32 v35, 16, v107
	v_mul_f32_e32 v33, v33, v35
	v_cvt_pk_bf16_f32 v33, v33, s0
	global_store_short v[148:149], v33, off offset:64
	v_lshl_add_u64 v[148:149], s[22:23], 0, v[58:59]
	v_lshlrev_b64 v[148:149], 11, v[148:149]
	v_lshl_add_u64 v[148:149], v[152:153], 0, v[148:149]
	v_add_f32_e32 v32, v21, v135
	v_lshlrev_b32_e32 v34, 16, v108
	v_mul_f32_e32 v32, v32, v34
	v_cvt_pk_bf16_f32 v32, v32, s0
	global_store_short v[148:149], v32, off
	v_add_f32_e32 v33, v5, v135
	v_lshlrev_b32_e32 v35, 16, v109
	v_mul_f32_e32 v33, v33, v35
	v_cvt_pk_bf16_f32 v33, v33, s0
	global_store_short v[148:149], v33, off offset:64
	v_lshl_add_u64 v[148:149], s[22:23], 0, v[60:61]
	v_lshlrev_b64 v[148:149], 11, v[148:149]
	v_lshl_add_u64 v[148:149], v[152:153], 0, v[148:149]
	v_add_f32_e32 v32, v22, v136
	v_lshlrev_b32_e32 v34, 16, v110
	v_mul_f32_e32 v32, v32, v34
	v_cvt_pk_bf16_f32 v32, v32, s0
	global_store_short v[148:149], v32, off
	v_add_f32_e32 v33, v6, v136
	v_lshlrev_b32_e32 v35, 16, v111
	v_mul_f32_e32 v33, v33, v35
	v_cvt_pk_bf16_f32 v33, v33, s0
	global_store_short v[148:149], v33, off offset:64
	v_lshl_add_u64 v[148:149], s[22:23], 0, v[62:63]
	v_lshlrev_b64 v[148:149], 11, v[148:149]
	v_lshl_add_u64 v[148:149], v[152:153], 0, v[148:149]
	v_add_f32_e32 v32, v23, v137
	v_lshlrev_b32_e32 v34, 16, v112
	v_mul_f32_e32 v32, v32, v34
	v_cvt_pk_bf16_f32 v32, v32, s0
	global_store_short v[148:149], v32, off
	v_add_f32_e32 v33, v7, v137
	v_lshlrev_b32_e32 v35, 16, v113
	v_mul_f32_e32 v33, v33, v35
	v_cvt_pk_bf16_f32 v33, v33, s0
	global_store_short v[148:149], v33, off offset:64
; DI unsigned pk2(float lo, float hi) { f32x2 v = {lo, hi}; bf16x2_t b = __builtin_convertvector(v, bf16x2_t); return __builtin_bit_cast(unsigned, b); }
; DI float bf2f(unsigned short u) { return __uint_as_float(((unsigned)u) << 16); }
; DI int crow(int i, int h) { return (i & 3) + 8 * (i >> 2) + 4 * h; }
; DI void phase_sgu(ArgsP AP, LAS unsigned char* lds) {
;     ...
;                 for (int i = 0; i < 16; ++i) { const int t = 32 * tb + crow(i, h), c = g * 128 + 32 * (cb0 + ci) + r32; const size_t row = r0 + t;
;                     const float mixed = acc[ci][i] + gbs[g * 128 + t]; const float uv = bf2f(UV[row * 2048 + c]);
;                     OA[row * DM + c] = (bf16)(pk2(uv * mixed, 0.f) & 0xffffu); }
;             __syncthreads();
	v_lshl_add_u64 v[148:149], s[22:23], 0, v[64:65]
	v_lshlrev_b64 v[148:149], 11, v[148:149]
	v_lshl_add_u64 v[148:149], v[152:153], 0, v[148:149]
	v_add_f32_e32 v32, v24, v138
	v_lshlrev_b32_e32 v34, 16, v114
	v_mul_f32_e32 v32, v32, v34
	v_cvt_pk_bf16_f32 v32, v32, s0
	global_store_short v[148:149], v32, off
	v_add_f32_e32 v33, v8, v138
	v_lshlrev_b32_e32 v35, 16, v115
	v_mul_f32_e32 v33, v33, v35
	v_cvt_pk_bf16_f32 v33, v33, s0
	global_store_short v[148:149], v33, off offset:64
	v_lshl_add_u64 v[148:149], s[22:23], 0, v[66:67]
	v_lshlrev_b64 v[148:149], 11, v[148:149]
	v_lshl_add_u64 v[148:149], v[152:153], 0, v[148:149]
	v_add_f32_e32 v32, v25, v139
	v_lshlrev_b32_e32 v34, 16, v116
	v_mul_f32_e32 v32, v32, v34
	v_cvt_pk_bf16_f32 v32, v32, s0
	global_store_short v[148:149], v32, off
	v_add_f32_e32 v33, v9, v139
	v_lshlrev_b32_e32 v35, 16, v117
	v_mul_f32_e32 v33, v33, v35
	v_cvt_pk_bf16_f32 v33, v33, s0
	global_store_short v[148:149], v33, off offset:64
	v_lshl_add_u64 v[148:149], s[22:23], 0, v[68:69]
	v_lshlrev_b64 v[148:149], 11, v[148:149]
	v_lshl_add_u64 v[148:149], v[152:153], 0, v[148:149]
	v_add_f32_e32 v32, v26, v140
	v_lshlrev_b32_e32 v34, 16, v118
	v_mul_f32_e32 v32, v32, v34
	v_cvt_pk_bf16_f32 v32, v32, s0
	global_store_short v[148:149], v32, off
	v_add_f32_e32 v33, v10, v140
	v_lshlrev_b32_e32 v35, 16, v119
	v_mul_f32_e32 v33, v33, v35
	v_cvt_pk_bf16_f32 v33, v33, s0
	global_store_short v[148:149], v33, off offset:64
	v_lshl_add_u64 v[148:149], s[22:23], 0, v[70:71]
	v_lshlrev_b64 v[148:149], 11, v[148:149]
	v_lshl_add_u64 v[148:149], v[152:153], 0, v[148:149]
	v_add_f32_e32 v32, v27, v141
	v_lshlrev_b32_e32 v34, 16, v120
	v_mul_f32_e32 v32, v32, v34
	v_cvt_pk_bf16_f32 v32, v32, s0
	global_store_short v[148:149], v32, off
	v_add_f32_e32 v33, v11, v141
	v_lshlrev_b32_e32 v35, 16, v121
	v_mul_f32_e32 v33, v33, v35
	v_cvt_pk_bf16_f32 v33, v33, s0
	global_store_short v[148:149], v33, off offset:64
	v_lshl_add_u64 v[148:149], s[22:23], 0, v[72:73]
	v_lshlrev_b64 v[148:149], 11, v[148:149]
	v_lshl_add_u64 v[148:149], v[152:153], 0, v[148:149]
	v_add_f32_e32 v32, v28, v142
	v_lshlrev_b32_e32 v34, 16, v122
	v_mul_f32_e32 v32, v32, v34
	v_cvt_pk_bf16_f32 v32, v32, s0
	global_store_short v[148:149], v32, off
	v_add_f32_e32 v33, v12, v142
	v_lshlrev_b32_e32 v35, 16, v123
	v_mul_f32_e32 v33, v33, v35
	v_cvt_pk_bf16_f32 v33, v33, s0
	global_store_short v[148:149], v33, off offset:64
	v_lshl_add_u64 v[148:149], s[22:23], 0, v[74:75]
	v_lshlrev_b64 v[148:149], 11, v[148:149]
	v_lshl_add_u64 v[148:149], v[152:153], 0, v[148:149]
	v_add_f32_e32 v32, v29, v143
	v_lshlrev_b32_e32 v34, 16, v124
	v_mul_f32_e32 v32, v32, v34
	v_cvt_pk_bf16_f32 v32, v32, s0
	global_store_short v[148:149], v32, off
	v_add_f32_e32 v33, v13, v143
	v_lshlrev_b32_e32 v35, 16, v125
	v_mul_f32_e32 v33, v33, v35
	v_cvt_pk_bf16_f32 v33, v33, s0
	global_store_short v[148:149], v33, off offset:64
	v_lshl_add_u64 v[148:149], s[22:23], 0, v[76:77]
	v_lshlrev_b64 v[148:149], 11, v[148:149]
	v_lshl_add_u64 v[148:149], v[152:153], 0, v[148:149]
	v_add_f32_e32 v32, v30, v144
	v_lshlrev_b32_e32 v34, 16, v126
	v_mul_f32_e32 v32, v32, v34
	v_cvt_pk_bf16_f32 v32, v32, s0
	global_store_short v[148:149], v32, off
	v_add_f32_e32 v33, v14, v144
	v_lshlrev_b32_e32 v35, 16, v127
	v_mul_f32_e32 v33, v33, v35
	v_cvt_pk_bf16_f32 v33, v33, s0
	global_store_short v[148:149], v33, off offset:64
	v_lshl_add_u64 v[148:149], s[22:23], 0, v[78:79]
	v_lshlrev_b64 v[148:149], 11, v[148:149]
	v_lshl_add_u64 v[148:149], v[152:153], 0, v[148:149]
	v_add_f32_e32 v32, v31, v145
	v_lshlrev_b32_e32 v34, 16, v128
	v_mul_f32_e32 v32, v32, v34
	v_cvt_pk_bf16_f32 v32, v32, s0
	global_store_short v[148:149], v32, off
	v_add_f32_e32 v33, v15, v145
	v_lshlrev_b32_e32 v35, 16, v129
	v_mul_f32_e32 v33, v33, v35
	v_cvt_pk_bf16_f32 v33, v33, s0
	global_store_short v[148:149], v33, off offset:64
	s_barrier
